# FFT second-input loads hoisted before the spectrum read-out; final-loop first-iteration loads issued before the scan steps and barrier; kv/gla_out item start round trips overlapped
# speedup vs baseline: 1.0068x; 1.0039x over previous
.LBB0_703:
	s_or_b64 exec, exec, s[2:3]
	s_waitcnt vmcnt(0)
	s_lshl_b64 s[98:99], s[28:29], 13
	s_lshl_b64 s[100:101], s[10:11], 13
	v_add_u32_e32 v152, 0, v24
	v_ashrrev_i32_e32 v153, 31, v152
	v_lshlrev_b64 v[148:149], 1, v[152:153]
	v_lshl_add_u64 v[150:151], s[30:31], 0, v[148:149]
	global_load_ushort v116, v[150:151], off
	v_add_u32_e32 v150, 0, v24
	v_ashrrev_i32_e32 v151, 31, v150
	v_lshl_add_u64 v[148:149], s[98:99], 0, v[150:151]
	v_lshl_add_u64 v[148:149], v[148:149], 1, s[0:1]
	global_load_ushort v117, v[148:149], off
	v_add_u32_e32 v150, 0, v24
	v_ashrrev_i32_e32 v151, 31, v150
	v_lshlrev_b64 v[148:149], 1, v[150:151]
	v_lshl_add_u64 v[148:149], s[86:87], 0, v[148:149]
	global_load_ushort v118, v[148:149], off
	v_add_u32_e32 v152, 0, v24
	v_add_u32_e32 v148, 0xe00, v152
	v_ashrrev_i32_e32 v149, 31, v148
	v_lshl_add_u64 v[150:151], s[98:99], 0, v[148:149]
	v_lshl_add_u64 v[150:151], v[150:151], 1, s[0:1]
	global_load_ushort v119, v[150:151], off
	v_add_u32_e32 v152, 0, v24
	v_ashrrev_i32_e32 v153, 31, v152
	v_lshl_add_u64 v[150:151], s[100:101], 0, v[152:153]
	v_lshl_add_u64 v[148:149], v[150:151], 1, s[0:1]
	global_load_ushort v120, v[148:149], off
	v_add_u32_e32 v152, 0, v24
	v_add_u32_e32 v150, 0x200, v152
	v_ashrrev_i32_e32 v151, 31, v150
	v_lshl_add_u64 v[148:149], s[98:99], 0, v[150:151]
	v_lshl_add_u64 v[148:149], v[148:149], 1, s[0:1]
	global_load_ushort v121, v[148:149], off
	v_add_u32_e32 v152, 0, v24
	v_add_u32_e32 v148, 0xe00, v152
	v_ashrrev_i32_e32 v149, 31, v148
	v_lshl_add_u64 v[150:151], s[100:101], 0, v[148:149]
	v_lshl_add_u64 v[150:151], v[150:151], 1, s[0:1]
	global_load_ushort v122, v[150:151], off
	v_add_u32_e32 v154, 0, v24
	v_add_u32_e32 v152, 0x200, v154
	v_ashrrev_i32_e32 v153, 31, v152
	v_lshlrev_b64 v[148:149], 1, v[152:153]
	v_lshl_add_u64 v[150:151], s[30:31], 0, v[148:149]
	global_load_ushort v123, v[150:151], off
	v_add_u32_e32 v154, 0, v24
	v_add_u32_e32 v152, 0x200, v154
	v_ashrrev_i32_e32 v153, 31, v152
	v_lshl_add_u64 v[150:151], s[100:101], 0, v[152:153]
	v_lshl_add_u64 v[148:149], v[150:151], 1, s[0:1]
	global_load_ushort v124, v[148:149], off
	v_add_u32_e32 v152, 0, v24
	v_add_u32_e32 v150, 0x400, v152
	v_ashrrev_i32_e32 v151, 31, v150
	v_lshl_add_u64 v[148:149], s[98:99], 0, v[150:151]
	v_lshl_add_u64 v[148:149], v[148:149], 1, s[0:1]
	global_load_ushort v125, v[148:149], off
	v_add_u32_e32 v152, 0, v24
	v_add_u32_e32 v150, 0x200, v152
	v_ashrrev_i32_e32 v151, 31, v150
	v_lshlrev_b64 v[148:149], 1, v[150:151]
	v_lshl_add_u64 v[148:149], s[86:87], 0, v[148:149]
	global_load_ushort v126, v[148:149], off
	v_add_u32_e32 v154, 0, v24
	v_add_u32_e32 v152, 0x400, v154
	v_ashrrev_i32_e32 v153, 31, v152
	v_lshlrev_b64 v[148:149], 1, v[152:153]
	v_lshl_add_u64 v[150:151], s[30:31], 0, v[148:149]
	global_load_ushort v127, v[150:151], off
	v_add_u32_e32 v152, 0, v24
	v_add_u32_e32 v150, 0x400, v152
	v_ashrrev_i32_e32 v151, 31, v150
	v_lshlrev_b64 v[148:149], 1, v[150:151]
	v_lshl_add_u64 v[148:149], s[86:87], 0, v[148:149]
	global_load_ushort v128, v[148:149], off
	v_add_u32_e32 v154, 0, v24
	v_add_u32_e32 v152, 0x400, v154
	v_ashrrev_i32_e32 v153, 31, v152
	v_lshl_add_u64 v[150:151], s[100:101], 0, v[152:153]
	v_lshl_add_u64 v[148:149], v[150:151], 1, s[0:1]
	global_load_ushort v129, v[148:149], off
	v_add_u32_e32 v152, 0, v24
	v_add_u32_e32 v150, 0x600, v152
	v_ashrrev_i32_e32 v151, 31, v150
	v_lshl_add_u64 v[148:149], s[98:99], 0, v[150:151]
	v_lshl_add_u64 v[148:149], v[148:149], 1, s[0:1]
	global_load_ushort v130, v[148:149], off
	v_add_u32_e32 v154, 0, v24
	v_add_u32_e32 v152, 0x600, v154
	v_ashrrev_i32_e32 v153, 31, v152
	v_lshlrev_b64 v[148:149], 1, v[152:153]
	v_lshl_add_u64 v[150:151], s[30:31], 0, v[148:149]
	global_load_ushort v131, v[150:151], off
	v_add_u32_e32 v154, 0, v24
	v_add_u32_e32 v152, 0x600, v154
	v_ashrrev_i32_e32 v153, 31, v152
	v_lshl_add_u64 v[150:151], s[100:101], 0, v[152:153]
	v_lshl_add_u64 v[148:149], v[150:151], 1, s[0:1]
	global_load_ushort v132, v[148:149], off
	v_add_u32_e32 v152, 0, v24
	v_add_u32_e32 v150, 0x600, v152
	v_ashrrev_i32_e32 v151, 31, v150
	v_lshlrev_b64 v[148:149], 1, v[150:151]
	v_lshl_add_u64 v[148:149], s[86:87], 0, v[148:149]
	global_load_ushort v133, v[148:149], off
	v_add_u32_e32 v152, 0, v24
	v_add_u32_e32 v150, 0x800, v152
	v_ashrrev_i32_e32 v151, 31, v150
	v_lshl_add_u64 v[148:149], s[98:99], 0, v[150:151]
	v_lshl_add_u64 v[148:149], v[148:149], 1, s[0:1]
	global_load_ushort v134, v[148:149], off
	v_add_u32_e32 v154, 0, v24
	v_add_u32_e32 v152, 0x800, v154
	v_ashrrev_i32_e32 v153, 31, v152
	v_lshlrev_b64 v[148:149], 1, v[152:153]
	v_lshl_add_u64 v[150:151], s[30:31], 0, v[148:149]
	global_load_ushort v135, v[150:151], off
	v_add_u32_e32 v154, 0, v24
	v_add_u32_e32 v152, 0x800, v154
	v_ashrrev_i32_e32 v153, 31, v152
	v_lshl_add_u64 v[150:151], s[100:101], 0, v[152:153]
	v_lshl_add_u64 v[148:149], v[150:151], 1, s[0:1]
	global_load_ushort v136, v[148:149], off
	v_add_u32_e32 v152, 0, v24
	v_add_u32_e32 v150, 0x800, v152
	v_ashrrev_i32_e32 v151, 31, v150
	v_lshlrev_b64 v[148:149], 1, v[150:151]
	v_lshl_add_u64 v[148:149], s[86:87], 0, v[148:149]
	global_load_ushort v137, v[148:149], off
	v_add_u32_e32 v152, 0, v24
	v_add_u32_e32 v150, 0xa00, v152
	v_ashrrev_i32_e32 v151, 31, v150
	v_lshl_add_u64 v[148:149], s[98:99], 0, v[150:151]
	v_lshl_add_u64 v[148:149], v[148:149], 1, s[0:1]
	global_load_ushort v138, v[148:149], off
	v_add_u32_e32 v154, 0, v24
	v_add_u32_e32 v152, 0xa00, v154
	v_ashrrev_i32_e32 v153, 31, v152
	v_lshlrev_b64 v[148:149], 1, v[152:153]
	v_lshl_add_u64 v[150:151], s[30:31], 0, v[148:149]
	global_load_ushort v139, v[150:151], off
	v_add_u32_e32 v154, 0, v24
	v_add_u32_e32 v152, 0xa00, v154
	v_ashrrev_i32_e32 v153, 31, v152
	v_lshl_add_u64 v[150:151], s[100:101], 0, v[152:153]
	v_lshl_add_u64 v[148:149], v[150:151], 1, s[0:1]
	global_load_ushort v140, v[148:149], off
	v_add_u32_e32 v152, 0, v24
	v_add_u32_e32 v150, 0xa00, v152
	v_ashrrev_i32_e32 v151, 31, v150
	v_lshlrev_b64 v[148:149], 1, v[150:151]
	v_lshl_add_u64 v[148:149], s[86:87], 0, v[148:149]
	global_load_ushort v141, v[148:149], off
	v_add_u32_e32 v152, 0, v24
	v_add_u32_e32 v150, 0xc00, v152
	v_ashrrev_i32_e32 v151, 31, v150
	v_lshl_add_u64 v[148:149], s[98:99], 0, v[150:151]
	v_lshl_add_u64 v[148:149], v[148:149], 1, s[0:1]
	global_load_ushort v142, v[148:149], off
	v_add_u32_e32 v154, 0, v24
	v_add_u32_e32 v152, 0xc00, v154
	v_ashrrev_i32_e32 v153, 31, v152
	v_lshlrev_b64 v[148:149], 1, v[152:153]
	v_lshl_add_u64 v[150:151], s[30:31], 0, v[148:149]
	global_load_ushort v143, v[150:151], off
	v_add_u32_e32 v152, 0, v24
	v_add_u32_e32 v150, 0xc00, v152
	v_ashrrev_i32_e32 v151, 31, v150
	v_lshlrev_b64 v[148:149], 1, v[150:151]
	v_lshl_add_u64 v[148:149], s[86:87], 0, v[148:149]
	global_load_ushort v144, v[148:149], off
	v_add_u32_e32 v154, 0, v24
	v_add_u32_e32 v152, 0xc00, v154
	v_ashrrev_i32_e32 v153, 31, v152
	v_lshl_add_u64 v[150:151], s[100:101], 0, v[152:153]
	v_lshl_add_u64 v[148:149], v[150:151], 1, s[0:1]
	global_load_ushort v145, v[148:149], off
	v_add_u32_e32 v154, 0, v24
	v_add_u32_e32 v152, 0xe00, v154
	v_ashrrev_i32_e32 v153, 31, v152
	v_lshlrev_b64 v[148:149], 1, v[152:153]
	v_lshl_add_u64 v[150:151], s[30:31], 0, v[148:149]
	global_load_ushort v146, v[150:151], off
	v_add_u32_e32 v152, 0, v24
	v_add_u32_e32 v150, 0xe00, v152
	v_ashrrev_i32_e32 v151, 31, v150
	v_lshlrev_b64 v[148:149], 1, v[150:151]
	v_lshl_add_u64 v[148:149], s[86:87], 0, v[148:149]
	global_load_ushort v147, v[148:149], off
	v_lshlrev_b32_e32 v220, 16, v168
	v_and_b32_e32 v221, 0xffff0000, v168
	v_bfe_u32 v222, v218, 16, 1
	v_bfe_u32 v223, v219, 16, 1
	v_add3_u32 v222, v218, v222, v234
	v_add3_u32 v223, v219, v223, v234
	v_lshrrev_b32_e32 v222, 16, v222
	v_and_or_b32 v222, v223, v235, v222
	global_store_dword v[226:227], v222, off
	v_pk_fma_f32 v[218:219], v[186:187], v[218:219], v[220:221]
	v_lshl_add_u64 v[226:227], v[226:227], 0, v[230:231]
	v_lshlrev_b32_e32 v220, 16, v169
	v_and_b32_e32 v221, 0xffff0000, v169
	v_bfe_u32 v222, v218, 16, 1
	v_bfe_u32 v223, v219, 16, 1
	v_add3_u32 v222, v218, v222, v234
	v_add3_u32 v223, v219, v223, v234
	v_lshrrev_b32_e32 v222, 16, v222
	v_and_or_b32 v222, v223, v235, v222
	global_store_dword v[226:227], v222, off
	v_pk_fma_f32 v[218:219], v[188:189], v[218:219], v[220:221]
	v_lshl_add_u64 v[226:227], v[226:227], 0, v[230:231]
	v_lshlrev_b32_e32 v220, 16, v170
	v_and_b32_e32 v221, 0xffff0000, v170
	v_bfe_u32 v222, v218, 16, 1
	v_bfe_u32 v223, v219, 16, 1
	v_add3_u32 v222, v218, v222, v234
	v_add3_u32 v223, v219, v223, v234
	v_lshrrev_b32_e32 v222, 16, v222
	v_and_or_b32 v222, v223, v235, v222
	global_store_dword v[226:227], v222, off
	v_pk_fma_f32 v[218:219], v[190:191], v[218:219], v[220:221]
	v_lshl_add_u64 v[226:227], v[226:227], 0, v[230:231]
	v_lshlrev_b32_e32 v220, 16, v171
	v_and_b32_e32 v221, 0xffff0000, v171
	v_bfe_u32 v222, v218, 16, 1
	v_bfe_u32 v223, v219, 16, 1
	v_add3_u32 v222, v218, v222, v234
	v_add3_u32 v223, v219, v223, v234
	v_lshrrev_b32_e32 v222, 16, v222
	v_and_or_b32 v222, v223, v235, v222
	global_store_dword v[226:227], v222, off
	v_pk_fma_f32 v[218:219], v[192:193], v[218:219], v[220:221]
	v_lshl_add_u64 v[226:227], v[226:227], 0, v[230:231]
	v_lshlrev_b32_e32 v220, 16, v172
	v_and_b32_e32 v221, 0xffff0000, v172
	v_bfe_u32 v222, v218, 16, 1
	v_bfe_u32 v223, v219, 16, 1
	v_add3_u32 v222, v218, v222, v234
	v_add3_u32 v223, v219, v223, v234
	v_lshrrev_b32_e32 v222, 16, v222
	v_and_or_b32 v222, v223, v235, v222
	global_store_dword v[226:227], v222, off
	v_pk_fma_f32 v[218:219], v[194:195], v[218:219], v[220:221]
	v_lshl_add_u64 v[226:227], v[226:227], 0, v[230:231]
	v_lshlrev_b32_e32 v220, 16, v173
	v_and_b32_e32 v221, 0xffff0000, v173
	v_bfe_u32 v222, v218, 16, 1
	v_bfe_u32 v223, v219, 16, 1
	v_add3_u32 v222, v218, v222, v234
	v_add3_u32 v223, v219, v223, v234
	v_lshrrev_b32_e32 v222, 16, v222
	v_and_or_b32 v222, v223, v235, v222
	global_store_dword v[226:227], v222, off
	v_pk_fma_f32 v[218:219], v[196:197], v[218:219], v[220:221]
	v_lshl_add_u64 v[226:227], v[226:227], 0, v[230:231]
	v_lshlrev_b32_e32 v220, 16, v174
	v_and_b32_e32 v221, 0xffff0000, v174
	v_bfe_u32 v222, v218, 16, 1
	v_bfe_u32 v223, v219, 16, 1
	v_add3_u32 v222, v218, v222, v234
	v_add3_u32 v223, v219, v223, v234
	v_lshrrev_b32_e32 v222, 16, v222
	v_and_or_b32 v222, v223, v235, v222
	global_store_dword v[226:227], v222, off
	v_pk_fma_f32 v[218:219], v[198:199], v[218:219], v[220:221]
	v_lshl_add_u64 v[226:227], v[226:227], 0, v[230:231]
	v_lshlrev_b32_e32 v220, 16, v175
	v_and_b32_e32 v221, 0xffff0000, v175
	v_bfe_u32 v222, v218, 16, 1
	v_bfe_u32 v223, v219, 16, 1
	v_add3_u32 v222, v218, v222, v234
	v_add3_u32 v223, v219, v223, v234
	v_lshrrev_b32_e32 v222, 16, v222
	v_and_or_b32 v222, v223, v235, v222
	global_store_dword v[226:227], v222, off
	v_pk_fma_f32 v[218:219], v[200:201], v[218:219], v[220:221]
	v_lshl_add_u64 v[226:227], v[226:227], 0, v[230:231]
	v_lshlrev_b32_e32 v220, 16, v176
	v_and_b32_e32 v221, 0xffff0000, v176
	v_bfe_u32 v222, v218, 16, 1
	v_bfe_u32 v223, v219, 16, 1
	v_add3_u32 v222, v218, v222, v234
	v_add3_u32 v223, v219, v223, v234
	v_lshrrev_b32_e32 v222, 16, v222
	v_and_or_b32 v222, v223, v235, v222
	global_store_dword v[226:227], v222, off
	v_pk_fma_f32 v[218:219], v[202:203], v[218:219], v[220:221]
	v_lshl_add_u64 v[226:227], v[226:227], 0, v[230:231]
	v_lshlrev_b32_e32 v220, 16, v177
	v_and_b32_e32 v221, 0xffff0000, v177
	v_bfe_u32 v222, v218, 16, 1
	v_bfe_u32 v223, v219, 16, 1
	v_add3_u32 v222, v218, v222, v234
	v_add3_u32 v223, v219, v223, v234
	v_lshrrev_b32_e32 v222, 16, v222
	v_and_or_b32 v222, v223, v235, v222
	global_store_dword v[226:227], v222, off
	v_pk_fma_f32 v[218:219], v[204:205], v[218:219], v[220:221]
	v_lshl_add_u64 v[226:227], v[226:227], 0, v[230:231]
	v_lshlrev_b32_e32 v220, 16, v180
	v_and_b32_e32 v221, 0xffff0000, v180
	v_bfe_u32 v222, v218, 16, 1
	v_bfe_u32 v223, v219, 16, 1
	v_add3_u32 v222, v218, v222, v234
	v_add3_u32 v223, v219, v223, v234
	v_lshrrev_b32_e32 v222, 16, v222
	v_and_or_b32 v222, v223, v235, v222
	global_store_dword v[226:227], v222, off
	v_pk_fma_f32 v[218:219], v[206:207], v[218:219], v[220:221]
	v_lshl_add_u64 v[226:227], v[226:227], 0, v[230:231]
	v_lshlrev_b32_e32 v220, 16, v181
	v_and_b32_e32 v221, 0xffff0000, v181
	v_bfe_u32 v222, v218, 16, 1
	v_bfe_u32 v223, v219, 16, 1
	v_add3_u32 v222, v218, v222, v234
	v_add3_u32 v223, v219, v223, v234
	v_lshrrev_b32_e32 v222, 16, v222
	v_and_or_b32 v222, v223, v235, v222
	global_store_dword v[226:227], v222, off
	v_pk_fma_f32 v[218:219], v[208:209], v[218:219], v[220:221]
	v_lshl_add_u64 v[226:227], v[226:227], 0, v[230:231]
	v_lshlrev_b32_e32 v220, 16, v182
	v_and_b32_e32 v221, 0xffff0000, v182
	v_bfe_u32 v222, v218, 16, 1
	v_bfe_u32 v223, v219, 16, 1
	v_add3_u32 v222, v218, v222, v234
	v_add3_u32 v223, v219, v223, v234
	v_lshrrev_b32_e32 v222, 16, v222
	v_and_or_b32 v222, v223, v235, v222
	global_store_dword v[226:227], v222, off
	v_pk_fma_f32 v[218:219], v[210:211], v[218:219], v[220:221]
	v_lshl_add_u64 v[226:227], v[226:227], 0, v[230:231]
	v_lshlrev_b32_e32 v220, 16, v183
	v_and_b32_e32 v221, 0xffff0000, v183
	v_bfe_u32 v222, v218, 16, 1
	v_bfe_u32 v223, v219, 16, 1
	v_add3_u32 v222, v218, v222, v234
	v_add3_u32 v223, v219, v223, v234
	v_lshrrev_b32_e32 v222, 16, v222
	v_and_or_b32 v222, v223, v235, v222
	global_store_dword v[226:227], v222, off
	v_pk_fma_f32 v[218:219], v[212:213], v[218:219], v[220:221]
	v_lshl_add_u64 v[226:227], v[226:227], 0, v[230:231]
	v_lshlrev_b32_e32 v220, 16, v184
	v_and_b32_e32 v221, 0xffff0000, v184
	v_bfe_u32 v222, v218, 16, 1
	v_bfe_u32 v223, v219, 16, 1
	v_add3_u32 v222, v218, v222, v234
	v_add3_u32 v223, v219, v223, v234
	v_lshrrev_b32_e32 v222, 16, v222
	v_and_or_b32 v222, v223, v235, v222
	global_store_dword v[226:227], v222, off
	v_pk_fma_f32 v[218:219], v[214:215], v[218:219], v[220:221]
	v_lshl_add_u64 v[226:227], v[226:227], 0, v[230:231]
	v_lshlrev_b32_e32 v220, 16, v185
	v_and_b32_e32 v221, 0xffff0000, v185
	v_bfe_u32 v222, v218, 16, 1
	v_bfe_u32 v223, v219, 16, 1
	v_add3_u32 v222, v218, v222, v234
	v_add3_u32 v223, v219, v223, v234
	v_lshrrev_b32_e32 v222, 16, v222
	v_and_or_b32 v222, v223, v235, v222
	global_store_dword v[226:227], v222, off
	v_pk_fma_f32 v[218:219], v[216:217], v[218:219], v[220:221]
	v_lshl_add_u64 v[226:227], v[226:227], 0, v[230:231]
	s_nop 0
	v_add_f32_e32 v0, 0, v8
	v_add_f32_e32 v0, v0, v9
	v_add_f32_e32 v0, v0, v10
	v_add_f32_e32 v0, v0, v11
	v_add_f32_e32 v0, v0, v4
	v_add_f32_e32 v0, v0, v5
	v_add_f32_e32 v0, v0, v6
	v_add_f32_e32 v0, v0, v7
	v_div_scale_f32 v3, s[2:3], v0, v0, 1.0
	v_rcp_f32_e32 v4, v3
	v_add_f32_e32 v2, 0, v16
	v_add_f32_e32 v2, v2, v17
	v_add_f32_e32 v2, v2, v18
	v_fma_f32 v5, -v3, v4, 1.0
	v_fmac_f32_e32 v4, v5, v4
	v_div_scale_f32 v5, vcc, 1.0, v0, 1.0
	v_add_f32_e32 v2, v2, v19
	v_mul_f32_e32 v6, v5, v4
	v_add_f32_e32 v2, v2, v12
	v_fma_f32 v7, -v3, v6, v5
	v_add_f32_e32 v2, v2, v13
	v_fmac_f32_e32 v6, v7, v4
	v_add_f32_e32 v2, v2, v14
	v_fma_f32 v3, -v3, v6, v5
	v_add_f32_e32 v2, v2, v15
	v_div_fmas_f32 v3, v3, v4, v6
	v_div_fixup_f32 v0, v3, v0, 1.0
	v_div_scale_f32 v3, s[2:3], v2, v2, 1.0
	v_rcp_f32_e32 v4, v3
	v_readlane_b32 s52, v253, 23
	s_lshl_b64 s[2:3], s[28:29], 2
	v_readlane_b32 s58, v253, 29
	v_fma_f32 v5, -v3, v4, 1.0
	v_fmac_f32_e32 v4, v5, v4
	v_div_scale_f32 v5, vcc, 1.0, v2, 1.0
	v_mul_f32_e32 v6, v5, v4
	v_fma_f32 v7, -v3, v6, v5
	v_fmac_f32_e32 v6, v7, v4
	v_fma_f32 v3, -v3, v6, v5
	v_readlane_b32 s59, v253, 30
	s_add_u32 s2, s58, s2
	v_div_fmas_f32 v3, v3, v4, v6
	s_addc_u32 s3, s59, s3
	v_div_fixup_f32 v25, v3, v2, 1.0
	s_waitcnt lgkmcnt(0)
	s_barrier
	global_load_dwordx2 v[2:3], v1, s[2:3]
	s_lshl_b64 s[2:3], s[28:29], 13
	s_lshl_b64 s[10:11], s[10:11], 13
	s_mov_b32 s20, 0
	s_mov_b64 s[12:13], -1
	v_readlane_b32 s53, v253, 24
	v_readlane_b32 s54, v253, 25
	v_readlane_b32 s55, v253, 26
	v_readlane_b32 s56, v253, 27
	v_readlane_b32 s57, v253, 28
	v_readlane_b32 s60, v253, 31
	v_readlane_b32 s61, v253, 32
	v_readlane_b32 s62, v253, 33
	v_readlane_b32 s63, v253, 34
	v_readlane_b32 s64, v253, 35
	v_readlane_b32 s65, v253, 36
	v_readlane_b32 s66, v253, 37
	v_readlane_b32 s67, v253, 38
.LBB0_704:
	s_cmp_eq_u32 s20, 0
	s_cbranch_scc1 .Lmy_ff_skip
	v_add_u32_e32 v152, s20, v24
	v_ashrrev_i32_e32 v153, 31, v152
	v_lshlrev_b64 v[148:149], 1, v[152:153]
	v_lshl_add_u64 v[150:151], s[30:31], 0, v[148:149]
	global_load_ushort v116, v[150:151], off
	v_add_u32_e32 v150, s20, v24
	v_ashrrev_i32_e32 v151, 31, v150
	v_lshl_add_u64 v[148:149], s[2:3], 0, v[150:151]
	v_lshl_add_u64 v[148:149], v[148:149], 1, s[0:1]
	global_load_ushort v117, v[148:149], off
	v_add_u32_e32 v150, s20, v24
	v_ashrrev_i32_e32 v151, 31, v150
	v_lshlrev_b64 v[148:149], 1, v[150:151]
	v_lshl_add_u64 v[148:149], s[86:87], 0, v[148:149]
	global_load_ushort v118, v[148:149], off
	v_add_u32_e32 v152, s20, v24
	v_add_u32_e32 v148, 0xe00, v152
	v_ashrrev_i32_e32 v149, 31, v148
	v_lshl_add_u64 v[150:151], s[2:3], 0, v[148:149]
	v_lshl_add_u64 v[150:151], v[150:151], 1, s[0:1]
	global_load_ushort v119, v[150:151], off
	v_add_u32_e32 v152, s20, v24
	v_ashrrev_i32_e32 v153, 31, v152
	v_lshl_add_u64 v[150:151], s[10:11], 0, v[152:153]
	v_lshl_add_u64 v[148:149], v[150:151], 1, s[0:1]
	global_load_ushort v120, v[148:149], off
	v_add_u32_e32 v152, s20, v24
	v_add_u32_e32 v150, 0x200, v152
	v_ashrrev_i32_e32 v151, 31, v150
	v_lshl_add_u64 v[148:149], s[2:3], 0, v[150:151]
	v_lshl_add_u64 v[148:149], v[148:149], 1, s[0:1]
	global_load_ushort v121, v[148:149], off
	v_add_u32_e32 v152, s20, v24
	v_add_u32_e32 v148, 0xe00, v152
	v_ashrrev_i32_e32 v149, 31, v148
	v_lshl_add_u64 v[150:151], s[10:11], 0, v[148:149]
	v_lshl_add_u64 v[150:151], v[150:151], 1, s[0:1]
	global_load_ushort v122, v[150:151], off
	v_add_u32_e32 v154, s20, v24
	v_add_u32_e32 v152, 0x200, v154
	v_ashrrev_i32_e32 v153, 31, v152
	v_lshlrev_b64 v[148:149], 1, v[152:153]
	v_lshl_add_u64 v[150:151], s[30:31], 0, v[148:149]
	global_load_ushort v123, v[150:151], off
	v_add_u32_e32 v154, s20, v24
	v_add_u32_e32 v152, 0x200, v154
	v_ashrrev_i32_e32 v153, 31, v152
	v_lshl_add_u64 v[150:151], s[10:11], 0, v[152:153]
	v_lshl_add_u64 v[148:149], v[150:151], 1, s[0:1]
	global_load_ushort v124, v[148:149], off
	v_add_u32_e32 v152, s20, v24
	v_add_u32_e32 v150, 0x400, v152
	v_ashrrev_i32_e32 v151, 31, v150
	v_lshl_add_u64 v[148:149], s[2:3], 0, v[150:151]
	v_lshl_add_u64 v[148:149], v[148:149], 1, s[0:1]
	global_load_ushort v125, v[148:149], off
	v_add_u32_e32 v152, s20, v24
	v_add_u32_e32 v150, 0x200, v152
	v_ashrrev_i32_e32 v151, 31, v150
	v_lshlrev_b64 v[148:149], 1, v[150:151]
	v_lshl_add_u64 v[148:149], s[86:87], 0, v[148:149]
	global_load_ushort v126, v[148:149], off
	v_add_u32_e32 v154, s20, v24
	v_add_u32_e32 v152, 0x400, v154
	v_ashrrev_i32_e32 v153, 31, v152
	v_lshlrev_b64 v[148:149], 1, v[152:153]
	v_lshl_add_u64 v[150:151], s[30:31], 0, v[148:149]
	global_load_ushort v127, v[150:151], off
	v_add_u32_e32 v152, s20, v24
	v_add_u32_e32 v150, 0x400, v152
	v_ashrrev_i32_e32 v151, 31, v150
	v_lshlrev_b64 v[148:149], 1, v[150:151]
	v_lshl_add_u64 v[148:149], s[86:87], 0, v[148:149]
	global_load_ushort v128, v[148:149], off
	v_add_u32_e32 v154, s20, v24
	v_add_u32_e32 v152, 0x400, v154
	v_ashrrev_i32_e32 v153, 31, v152
	v_lshl_add_u64 v[150:151], s[10:11], 0, v[152:153]
	v_lshl_add_u64 v[148:149], v[150:151], 1, s[0:1]
	global_load_ushort v129, v[148:149], off
	v_add_u32_e32 v152, s20, v24
	v_add_u32_e32 v150, 0x600, v152
	v_ashrrev_i32_e32 v151, 31, v150
	v_lshl_add_u64 v[148:149], s[2:3], 0, v[150:151]
	v_lshl_add_u64 v[148:149], v[148:149], 1, s[0:1]
	global_load_ushort v130, v[148:149], off
	v_add_u32_e32 v154, s20, v24
	v_add_u32_e32 v152, 0x600, v154
	v_ashrrev_i32_e32 v153, 31, v152
	v_lshlrev_b64 v[148:149], 1, v[152:153]
	v_lshl_add_u64 v[150:151], s[30:31], 0, v[148:149]
	global_load_ushort v131, v[150:151], off
	v_add_u32_e32 v154, s20, v24
	v_add_u32_e32 v152, 0x600, v154
	v_ashrrev_i32_e32 v153, 31, v152
	v_lshl_add_u64 v[150:151], s[10:11], 0, v[152:153]
	v_lshl_add_u64 v[148:149], v[150:151], 1, s[0:1]
	global_load_ushort v132, v[148:149], off
	v_add_u32_e32 v152, s20, v24
	v_add_u32_e32 v150, 0x600, v152
	v_ashrrev_i32_e32 v151, 31, v150
	v_lshlrev_b64 v[148:149], 1, v[150:151]
	v_lshl_add_u64 v[148:149], s[86:87], 0, v[148:149]
	global_load_ushort v133, v[148:149], off
	v_add_u32_e32 v152, s20, v24
	v_add_u32_e32 v150, 0x800, v152
	v_ashrrev_i32_e32 v151, 31, v150
	v_lshl_add_u64 v[148:149], s[2:3], 0, v[150:151]
	v_lshl_add_u64 v[148:149], v[148:149], 1, s[0:1]
	global_load_ushort v134, v[148:149], off
	v_add_u32_e32 v154, s20, v24
	v_add_u32_e32 v152, 0x800, v154
	v_ashrrev_i32_e32 v153, 31, v152
	v_lshlrev_b64 v[148:149], 1, v[152:153]
	v_lshl_add_u64 v[150:151], s[30:31], 0, v[148:149]
	global_load_ushort v135, v[150:151], off
	v_add_u32_e32 v154, s20, v24
	v_add_u32_e32 v152, 0x800, v154
	v_ashrrev_i32_e32 v153, 31, v152
	v_lshl_add_u64 v[150:151], s[10:11], 0, v[152:153]
	v_lshl_add_u64 v[148:149], v[150:151], 1, s[0:1]
	global_load_ushort v136, v[148:149], off
	v_add_u32_e32 v152, s20, v24
	v_add_u32_e32 v150, 0x800, v152
	v_ashrrev_i32_e32 v151, 31, v150
	v_lshlrev_b64 v[148:149], 1, v[150:151]
	v_lshl_add_u64 v[148:149], s[86:87], 0, v[148:149]
	global_load_ushort v137, v[148:149], off
	v_add_u32_e32 v152, s20, v24
	v_add_u32_e32 v150, 0xa00, v152
	v_ashrrev_i32_e32 v151, 31, v150
	v_lshl_add_u64 v[148:149], s[2:3], 0, v[150:151]
	v_lshl_add_u64 v[148:149], v[148:149], 1, s[0:1]
	global_load_ushort v138, v[148:149], off
	v_add_u32_e32 v154, s20, v24
	v_add_u32_e32 v152, 0xa00, v154
	v_ashrrev_i32_e32 v153, 31, v152
	v_lshlrev_b64 v[148:149], 1, v[152:153]
	v_lshl_add_u64 v[150:151], s[30:31], 0, v[148:149]
	global_load_ushort v139, v[150:151], off
	v_add_u32_e32 v154, s20, v24
	v_add_u32_e32 v152, 0xa00, v154
	v_ashrrev_i32_e32 v153, 31, v152
	v_lshl_add_u64 v[150:151], s[10:11], 0, v[152:153]
	v_lshl_add_u64 v[148:149], v[150:151], 1, s[0:1]
	global_load_ushort v140, v[148:149], off
	v_add_u32_e32 v152, s20, v24
	v_add_u32_e32 v150, 0xa00, v152
	v_ashrrev_i32_e32 v151, 31, v150
	v_lshlrev_b64 v[148:149], 1, v[150:151]
	v_lshl_add_u64 v[148:149], s[86:87], 0, v[148:149]
	global_load_ushort v141, v[148:149], off
	v_add_u32_e32 v152, s20, v24
	v_add_u32_e32 v150, 0xc00, v152
	v_ashrrev_i32_e32 v151, 31, v150
	v_lshl_add_u64 v[148:149], s[2:3], 0, v[150:151]
	v_lshl_add_u64 v[148:149], v[148:149], 1, s[0:1]
	global_load_ushort v142, v[148:149], off
	v_add_u32_e32 v154, s20, v24
	v_add_u32_e32 v152, 0xc00, v154
	v_ashrrev_i32_e32 v153, 31, v152
	v_lshlrev_b64 v[148:149], 1, v[152:153]
	v_lshl_add_u64 v[150:151], s[30:31], 0, v[148:149]
	global_load_ushort v143, v[150:151], off
	v_add_u32_e32 v152, s20, v24
	v_add_u32_e32 v150, 0xc00, v152
	v_ashrrev_i32_e32 v151, 31, v150
	v_lshlrev_b64 v[148:149], 1, v[150:151]
	v_lshl_add_u64 v[148:149], s[86:87], 0, v[148:149]
	global_load_ushort v144, v[148:149], off
	v_add_u32_e32 v154, s20, v24
	v_add_u32_e32 v152, 0xc00, v154
	v_ashrrev_i32_e32 v153, 31, v152
	v_lshl_add_u64 v[150:151], s[10:11], 0, v[152:153]
	v_lshl_add_u64 v[148:149], v[150:151], 1, s[0:1]
	global_load_ushort v145, v[148:149], off
	v_add_u32_e32 v154, s20, v24
	v_add_u32_e32 v152, 0xe00, v154
	v_ashrrev_i32_e32 v153, 31, v152
	v_lshlrev_b64 v[148:149], 1, v[152:153]
	v_lshl_add_u64 v[150:151], s[30:31], 0, v[148:149]
	global_load_ushort v146, v[150:151], off
	v_add_u32_e32 v152, s20, v24
	v_add_u32_e32 v150, 0xe00, v152
	v_ashrrev_i32_e32 v151, 31, v150
	v_lshlrev_b64 v[148:149], 1, v[150:151]
	v_lshl_add_u64 v[148:149], s[86:87], 0, v[148:149]
	global_load_ushort v147, v[148:149], off
.Lmy_ff_skip:
	s_waitcnt vmcnt(0)
	v_add_u32_e32 v82, s20, v24
	v_ashrrev_i32_e32 v83, 31, v82
	v_lshlrev_b64 v[4:5], 1, v[82:83]
	v_lshl_add_u64 v[20:21], s[30:31], 0, v[4:5]
	v_lshl_add_u64 v[6:7], s[2:3], 0, v[82:83]
	v_lshl_add_u64 v[4:5], s[86:87], 0, v[4:5]
	v_lshl_add_u64 v[6:7], v[6:7], 1, s[0:1]
	v_add_u32_e32 v54, 0xe00, v82
	v_ashrrev_i32_e32 v55, 31, v54
	v_lshl_add_u64 v[80:81], s[2:3], 0, v[54:55]
	v_lshl_add_u64 v[8:9], s[10:11], 0, v[82:83]
	v_lshl_add_u64 v[80:81], v[80:81], 1, s[0:1]
	v_add_u32_e32 v42, 0x200, v82
	v_ashrrev_i32_e32 v43, 31, v42
	v_lshl_add_u64 v[114:115], s[10:11], 0, v[54:55]
	v_lshl_add_u64 v[114:115], v[114:115], 1, s[0:1]
	v_add_u32_e32 v44, 0x400, v82
	v_ashrrev_i32_e32 v45, 31, v44
	v_add_u32_e32 v46, 0x600, v82
	v_ashrrev_i32_e32 v47, 31, v46
	v_add_u32_e32 v48, 0x800, v82
	v_ashrrev_i32_e32 v49, 31, v48
	v_add_u32_e32 v50, 0xa00, v82
	v_ashrrev_i32_e32 v51, 31, v50
	v_add_u32_e32 v52, 0xc00, v82
	v_ashrrev_i32_e32 v53, 31, v52
	v_lshl_add_u64 v[40:41], s[10:11], 0, v[52:53]
	v_lshl_add_u32 v111, s20, 3, v90
	s_movk_i32 s20, 0x1000
	s_and_b64 vcc, exec, s[12:13]
	s_mov_b64 s[12:13], 0
	v_lshlrev_b32_e32 v57, 16, v116
	v_ashrrev_i32_e32 v81, 5, v82
	v_lshl_add_u32 v81, v81, 3, v111
	ds_read_b64 v[82:83], v81
	s_waitcnt lgkmcnt(0)
	v_mul_f32_e32 v81, 0x38800000, v82
	v_mul_f32_e32 v81, v0, v81
	v_fmac_f32_e32 v81, v2, v57
	v_lshlrev_b32_e32 v73, 16, v117
	v_lshl_add_u64 v[6:7], v[8:9], 1, s[0:1]
	v_lshl_add_u64 v[8:9], s[2:3], 0, v[42:43]
	v_lshl_add_u64 v[8:9], v[8:9], 1, s[0:1]
	v_mul_f32_e32 v57, v81, v73
	v_bfe_u32 v73, v57, 16, 1
	v_add3_u32 v57, v57, v73, s45
	v_lshlrev_b32_e32 v56, 16, v118
	v_lshlrev_b32_e32 v80, 16, v119
	v_lshl_add_u64 v[10:11], s[10:11], 0, v[42:43]
	v_lshlrev_b32_e32 v65, 16, v120
	v_lshlrev_b64 v[6:7], 1, v[42:43]
	v_lshl_add_u64 v[22:23], s[30:31], 0, v[6:7]
	v_lshl_add_u64 v[6:7], s[86:87], 0, v[6:7]
	v_lshlrev_b32_e32 v74, 16, v121
	v_lshl_add_u64 v[8:9], v[10:11], 1, s[0:1]
	v_lshl_add_u64 v[10:11], s[2:3], 0, v[44:45]
	v_lshl_add_u64 v[10:11], v[10:11], 1, s[0:1]
	v_lshlrev_b32_e32 v72, 16, v122
	v_lshlrev_b32_e32 v58, 16, v123
	v_lshlrev_b32_e32 v66, 16, v124
	v_lshlrev_b64 v[8:9], 1, v[44:45]
	v_lshl_add_u64 v[30:31], s[30:31], 0, v[8:9]
	v_lshl_add_u64 v[8:9], s[86:87], 0, v[8:9]
	v_lshlrev_b32_e32 v75, 16, v125
	v_lshlrev_b32_e32 v43, 16, v126
	v_lshl_add_u64 v[12:13], s[10:11], 0, v[44:45]
	v_lshl_add_u64 v[10:11], v[12:13], 1, s[0:1]
	v_lshl_add_u64 v[12:13], s[2:3], 0, v[46:47]
	v_lshl_add_u64 v[12:13], v[12:13], 1, s[0:1]
	v_lshlrev_b32_e32 v59, 16, v127
	s_nop 0
	s_nop 0
	v_lshlrev_b32_e32 v45, 16, v128
	v_lshl_add_u64 v[14:15], s[10:11], 0, v[46:47]
	v_lshlrev_b32_e32 v67, 16, v129
	v_lshlrev_b64 v[10:11], 1, v[46:47]
	v_lshlrev_b32_e32 v76, 16, v130
	v_lshl_add_u64 v[32:33], s[30:31], 0, v[10:11]
	v_lshl_add_u64 v[10:11], s[86:87], 0, v[10:11]
	v_lshl_add_u64 v[12:13], v[14:15], 1, s[0:1]
	v_lshl_add_u64 v[14:15], s[2:3], 0, v[48:49]
	v_lshl_add_u64 v[14:15], v[14:15], 1, s[0:1]
	v_lshlrev_b32_e32 v60, 16, v131
	s_nop 0
	v_lshlrev_b32_e32 v68, 16, v132
	v_lshlrev_b64 v[12:13], 1, v[48:49]
	v_lshl_add_u64 v[34:35], s[30:31], 0, v[12:13]
	v_lshl_add_u64 v[12:13], s[86:87], 0, v[12:13]
	v_lshlrev_b32_e32 v47, 16, v133
	v_lshl_add_u64 v[16:17], s[10:11], 0, v[48:49]
	v_lshlrev_b32_e32 v77, 16, v134
	v_lshl_add_u64 v[14:15], v[16:17], 1, s[0:1]
	v_lshl_add_u64 v[16:17], s[2:3], 0, v[50:51]
	v_lshl_add_u64 v[16:17], v[16:17], 1, s[0:1]
	v_lshlrev_b32_e32 v61, 16, v135
	s_nop 0
	v_lshlrev_b32_e32 v69, 16, v136
	v_lshlrev_b64 v[14:15], 1, v[50:51]
	v_lshlrev_b32_e32 v49, 16, v137
	v_lshl_add_u64 v[18:19], s[10:11], 0, v[50:51]
	v_lshlrev_b32_e32 v78, 16, v138
	v_lshl_add_u64 v[36:37], s[30:31], 0, v[14:15]
	v_lshl_add_u64 v[14:15], s[86:87], 0, v[14:15]
	v_lshl_add_u64 v[16:17], v[18:19], 1, s[0:1]
	v_lshl_add_u64 v[18:19], s[2:3], 0, v[52:53]
	v_lshl_add_u64 v[18:19], v[18:19], 1, s[0:1]
	v_lshlrev_b32_e32 v62, 16, v139
	s_nop 0
	v_lshlrev_b32_e32 v70, 16, v140
	v_lshlrev_b64 v[16:17], 1, v[52:53]
	v_lshlrev_b32_e32 v51, 16, v141
	v_lshl_add_u64 v[38:39], s[30:31], 0, v[16:17]
	v_lshl_add_u64 v[16:17], s[86:87], 0, v[16:17]
	v_lshlrev_b32_e32 v79, 16, v142
	v_lshl_add_u64 v[18:19], v[40:41], 1, s[0:1]
	v_lshlrev_b32_e32 v63, 16, v143
	s_nop 0
	v_lshlrev_b32_e32 v53, 16, v144
	v_lshlrev_b32_e32 v71, 16, v145
	v_lshlrev_b64 v[18:19], 1, v[54:55]
	v_lshl_add_u64 v[40:41], s[30:31], 0, v[18:19]
	v_lshl_add_u64 v[18:19], s[86:87], 0, v[18:19]
	v_lshlrev_b32_e32 v64, 16, v146
	v_lshlrev_b32_e32 v55, 16, v147
	global_store_short_d16_hi v[20:21], v57, off
	v_mul_f32_e32 v20, 0x38800000, v83
	v_mul_f32_e32 v20, v25, v20
	v_fmac_f32_e32 v20, v3, v56
	v_mul_f32_e32 v20, v20, v65
	v_bfe_u32 v21, v20, 16, 1
	v_add3_u32 v20, v20, v21, s45
	global_store_short_d16_hi v[4:5], v20, off
	v_ashrrev_i32_e32 v4, 5, v42
	v_lshl_add_u32 v4, v4, 3, v111
	ds_read_b64 v[4:5], v4 offset:4096
	s_waitcnt lgkmcnt(0)
	v_mul_f32_e32 v4, 0x38800000, v4
	v_mul_f32_e32 v4, v0, v4
	v_fmac_f32_e32 v4, v2, v58
	v_mul_f32_e32 v4, v4, v74
	v_bfe_u32 v20, v4, 16, 1
	v_add3_u32 v4, v4, v20, s45
	global_store_short_d16_hi v[22:23], v4, off
	v_mul_f32_e32 v4, 0x38800000, v5
	v_mul_f32_e32 v4, v25, v4
	v_fmac_f32_e32 v4, v3, v43
	v_mul_f32_e32 v4, v4, v66
	v_bfe_u32 v5, v4, 16, 1
	v_add3_u32 v4, v4, v5, s45
	global_store_short_d16_hi v[6:7], v4, off
	v_ashrrev_i32_e32 v4, 5, v44
	v_lshl_add_u32 v4, v4, 3, v111
	ds_read_b64 v[4:5], v4 offset:8192
	s_waitcnt lgkmcnt(0)
	v_mul_f32_e32 v4, 0x38800000, v4
	v_mul_f32_e32 v4, v0, v4
	v_fmac_f32_e32 v4, v2, v59
	v_mul_f32_e32 v4, v4, v75
	v_bfe_u32 v6, v4, 16, 1
	v_add3_u32 v4, v4, v6, s45
	global_store_short_d16_hi v[30:31], v4, off
	v_mul_f32_e32 v4, 0x38800000, v5
	v_mul_f32_e32 v4, v25, v4
	v_fmac_f32_e32 v4, v3, v45
	v_mul_f32_e32 v4, v4, v67
	v_bfe_u32 v5, v4, 16, 1
	v_add3_u32 v4, v4, v5, s45
	global_store_short_d16_hi v[8:9], v4, off
	v_ashrrev_i32_e32 v4, 5, v46
	v_lshl_add_u32 v4, v4, 3, v111
	ds_read_b64 v[4:5], v4 offset:12288
	s_waitcnt lgkmcnt(0)
	v_mul_f32_e32 v4, 0x38800000, v4
	v_mul_f32_e32 v4, v0, v4
	v_fmac_f32_e32 v4, v2, v60
	v_mul_f32_e32 v4, v4, v76
	v_bfe_u32 v6, v4, 16, 1
	v_add3_u32 v4, v4, v6, s45
	global_store_short_d16_hi v[32:33], v4, off
	v_mul_f32_e32 v4, 0x38800000, v5
	v_mul_f32_e32 v4, v25, v4
	v_fmac_f32_e32 v4, v3, v47
	v_mul_f32_e32 v4, v4, v68
	v_bfe_u32 v5, v4, 16, 1
	v_add3_u32 v4, v4, v5, s45
	global_store_short_d16_hi v[10:11], v4, off
	v_ashrrev_i32_e32 v4, 5, v48
	v_lshl_add_u32 v4, v4, 3, v111
	ds_read_b64 v[4:5], v4 offset:16384
	s_waitcnt lgkmcnt(0)
	v_mul_f32_e32 v4, 0x38800000, v4
	v_mul_f32_e32 v4, v0, v4
	v_fmac_f32_e32 v4, v2, v61
	v_mul_f32_e32 v4, v4, v77
	v_bfe_u32 v6, v4, 16, 1
	v_add3_u32 v4, v4, v6, s45
	global_store_short_d16_hi v[34:35], v4, off
	v_mul_f32_e32 v4, 0x38800000, v5
	v_mul_f32_e32 v4, v25, v4
	v_fmac_f32_e32 v4, v3, v49
	v_mul_f32_e32 v4, v4, v69
	v_bfe_u32 v5, v4, 16, 1
	v_add3_u32 v4, v4, v5, s45
	global_store_short_d16_hi v[12:13], v4, off
	v_ashrrev_i32_e32 v4, 5, v50
	v_lshl_add_u32 v4, v4, 3, v111
	ds_read_b64 v[4:5], v4 offset:20480
	s_waitcnt lgkmcnt(0)
	v_mul_f32_e32 v4, 0x38800000, v4
	v_mul_f32_e32 v4, v0, v4
	v_fmac_f32_e32 v4, v2, v62
	v_mul_f32_e32 v4, v4, v78
	v_bfe_u32 v6, v4, 16, 1
	v_add3_u32 v4, v4, v6, s45
	global_store_short_d16_hi v[36:37], v4, off
	v_mul_f32_e32 v4, 0x38800000, v5
	v_mul_f32_e32 v4, v25, v4
	v_fmac_f32_e32 v4, v3, v51
	v_mul_f32_e32 v4, v4, v70
	v_bfe_u32 v5, v4, 16, 1
	v_add3_u32 v4, v4, v5, s45
	global_store_short_d16_hi v[14:15], v4, off
	v_ashrrev_i32_e32 v4, 5, v52
	v_lshl_add_u32 v4, v4, 3, v111
	ds_read_b64 v[4:5], v4 offset:24576
	s_waitcnt lgkmcnt(0)
	v_mul_f32_e32 v4, 0x38800000, v4
	v_mul_f32_e32 v4, v0, v4
	v_fmac_f32_e32 v4, v2, v63
	v_mul_f32_e32 v4, v4, v79
	v_bfe_u32 v6, v4, 16, 1
	v_add3_u32 v4, v4, v6, s45
	global_store_short_d16_hi v[38:39], v4, off
	v_mul_f32_e32 v4, 0x38800000, v5
	v_mul_f32_e32 v4, v25, v4
	v_fmac_f32_e32 v4, v3, v53
	v_mul_f32_e32 v4, v4, v71
	v_bfe_u32 v5, v4, 16, 1
	v_add3_u32 v4, v4, v5, s45
	global_store_short_d16_hi v[16:17], v4, off
	v_ashrrev_i32_e32 v4, 5, v54
	v_lshl_add_u32 v4, v4, 3, v111
	ds_read_b64 v[4:5], v4 offset:28672
	s_waitcnt lgkmcnt(0)
	v_mul_f32_e32 v4, 0x38800000, v4
	v_mul_f32_e32 v4, v0, v4
	v_fmac_f32_e32 v4, v2, v64
	v_mul_f32_e32 v4, v4, v80
	v_bfe_u32 v6, v4, 16, 1
	v_add3_u32 v4, v4, v6, s45
	global_store_short_d16_hi v[40:41], v4, off
	v_mul_f32_e32 v4, 0x38800000, v5
	v_mul_f32_e32 v4, v25, v4
	v_fmac_f32_e32 v4, v3, v55
	v_mul_f32_e32 v4, v4, v72
	v_bfe_u32 v5, v4, 16, 1
	v_add3_u32 v4, v4, v5, s45
	global_store_short_d16_hi v[18:19], v4, off
	s_cbranch_vccnz .LBB0_704
	v_readlane_b32 s2, v253, 3
	s_add_i32 s33, s33, s2
	s_cmpk_gt_i32 s33, 0x1ff
	s_barrier
	v_readlane_b32 s3, v253, 4
	s_cbranch_scc0 .LBB0_617
